# tile move + one-sided barrier waits (prep->phaseA for GEMM blocks, phaseA->phaseB for scan blocks) + pool history loads batched; all edits padded to keep code offsets mod 64
# speedup vs baseline: 1.0094x; 1.0094x over previous
; __device__ __forceinline__ unsigned xb_ld(unsigned* p)              { return __hip_atomic_load(p, __ATOMIC_RELAXED, __HIP_MEMORY_SCOPE_AGENT); }
; __device__ __forceinline__ unsigned xb_add(unsigned* p, unsigned v) { return __hip_atomic_fetch_add(p, v, __ATOMIC_RELAXED, __HIP_MEMORY_SCOPE_AGENT); }
; #define XB_SPIN(cond, bar) do { unsigned _sp = 0; while (cond) { __builtin_amdgcn_s_sleep(1); \
;     if ((++_sp & 255u) == 0u) { if (xb_ld(&(bar)[XB_TMO])) break; if (_sp > XB_SPIN_CAP) { atomicAdd(&(bar)[XB_TMO], 1u); break; } } } } while (0)
; __device__ __forceinline__ void xcd_barrier(const XcdBarrier& b) {
;     ...
;         const unsigned old = xb_add(&bar[XB_XSUB(b.x)], 1u);
;         const unsigned gen = old / nloc;
;         if (old + 1u == (gen + 1u) * nloc) {
;             __builtin_amdgcn_fence(__ATOMIC_RELEASE, "agent");
;             asm volatile("s_waitcnt vmcnt(0)" ::: "memory");
;             const unsigned og = xb_add(&bar[XB_TOP], 1u);
;             const unsigned tg = og / nx;
;             if (og + 1u == (tg + 1u) * nx) xb_add(&bar[XB_TOPGEN], 1u);
;             else XB_SPIN(xb_ld(&bar[XB_TOPGEN]) == tg, bar);
;             __builtin_amdgcn_fence(__ATOMIC_ACQUIRE, "agent");
;             xb_add(&bar[XB_XGEN(b.x)], 1u);
;             asm volatile("s_waitcnt vmcnt(0)" ::: "memory");
;         } else {
;             XB_SPIN(xb_ld(&bar[XB_XGEN(b.x)]) == gen, bar);
.Lb2wait_l0:
	s_nop 0
	s_nop 0
	s_nop 0
	s_nop 0
	s_nop 0
	s_nop 0
	s_nop 0
	s_nop 0
	s_nop 0
	s_nop 0
	s_nop 0
	s_nop 0
	v_mov_b32_e32 v0, 0x2000
	global_load_dword v0, v0, s[4:5] offset:1024 sc1
	s_add_u32 s52, s4, 0x2400
	s_addc_u32 s53, s5, 0
	s_waitcnt vmcnt(0)
	v_cmp_eq_u32_e32 vcc, v0, v1
	s_and_saveexec_b64 s[10:11], vcc
	s_cbranch_execz .LBB0_538
	s_mov_b32 s0, 1
	s_mov_b64 s[62:63], 0
	v_mov_b32_e32 v0, 0
	s_branch .LBB0_529

; __device__ __forceinline__ int xcd_remap(int L, int nwg) {
;     const int q = nwg >> 3, r = nwg & 7, xcd = L & 7, off = L >> 3;
;     return (xcd < r ? xcd * (q + 1) : r * (q + 1) + (xcd - r) * q) + off;
; }
;     __device__ __forceinline__ bool next(int i, Unit& u) {
;     ...
;         } else { L = i * G + c; if (L >= nwg) return false; L = xcd_remap(L, nwg); }
;         int q; map_tile(L, nq, 65, u.pm, q);
;         if (set == 0) u.pn = q < 13 ? 4 + q : 26 + (q - 13);
;         else u.pn = q < 4 ? q : (q < 13 ? 17 + (q - 4) : 31 + (q - 13));
.LBB0_1265:
	s_cmp_gt_i32 s92, 63
	s_cselect_b64 s[4:5], -1, 0
	s_mov_b64 s[2:3], -1
	s_and_b64 vcc, exec, s[4:5]
	s_cbranch_vccz .LBB0_1380
	s_mov_b64 s[0:1], src_shared_base
	s_getreg_b32 s0, hwreg(HW_REG_HW_ID, 0, 6)
	s_and_b32 s0, s0, 63
	s_lshl_b32 s0, s0, 2
	s_add_i32 s0, s0, 0
	s_add_i32 s0, s0, 0x20100
	v_mov_b32_e32 v0, s0
	v_mov_b32_e32 v1, s1
	flat_load_dword v0, v[0:1] sc0 sc1
	s_waitcnt vmcnt(0)
	s_sub_i32 s0, s92, 64
	s_cmpk_lt_u32 s0, 0xb2c
	s_cselect_b64 s[8:9], -1, 0
	s_cmpk_gt_u32 s0, 0xb2b
	s_waitcnt lgkmcnt(0)
	v_readfirstlane_b32 s1, v0
	s_nop 1
	v_lshl_or_b32 v8, s1, 6, v214
	s_nop 0
	v_readfirstlane_b32 s1, v8
	s_cbranch_scc1 .LBB0_1275
	s_and_b32 s2, s92, 7
	s_mul_i32 s3, s2, 0x165
	s_min_u32 s2, s2, 4
	s_add_i32 s2, s3, s2
	s_nop 0
	s_lshr_b32 s3, s0, 3
	s_add_i32 s2, s2, s3
	s_bfe_u32 s3, s2, 0xb0005
	s_mulk_i32 s3, 0x2e8c
	s_lshr_b32 s3, s3, 17
	s_lshl_b32 s6, s3, 3
	s_sub_i32 s7, 0x41, s6
	s_mulk_i32 s3, 0x160
	s_min_u32 s7, s7, 8
	s_sub_i32 s10, s2, s3
	s_and_b32 s2, s10, 0xffff
	v_cvt_f32_ubyte0_e32 v1, s7
	v_cvt_f32_u32_e32 v0, s2
	v_rcp_iflag_f32_e32 v2, v1
	s_nop 0
	v_mul_f32_e32 v2, v0, v2
	v_trunc_f32_e32 v2, v2
	v_cvt_u32_f32_e32 v3, v2
	v_fma_f32 v0, -v2, v1, v0
	v_cmp_ge_f32_e64 s[2:3], |v0|, v1
	s_cmp_lg_u64 s[2:3], 0
	v_readfirstlane_b32 s11, v3
	s_addc_u32 s3, s11, 0
	s_and_b32 s2, s3, 0xffff
	s_mul_i32 s3, s3, s7
	s_sub_i32 s3, s10, s3
	s_add_i32 s3, s3, s6
	s_cmp_lt_u32 s2, 4
	s_cbranch_scc1 .LBB0_1274
	s_cmp_gt_u32 s2, 12
	s_cbranch_scc0 .LBB0_1270
	s_add_i32 s10, s2, 15
	s_mov_b64 s[6:7], 0
	s_branch .LBB0_1271

; __device__ __forceinline__ int xcd_remap(int L, int nwg) {
;     const int q = nwg >> 3, r = nwg & 7, xcd = L & 7, off = L >> 3;
;     return (xcd < r ? xcd * (q + 1) : r * (q + 1) + (xcd - r) * q) + off;
; }
;     __device__ __forceinline__ bool next(int i, Unit& u) {
;     ...
;         } else { L = i * G + c; if (L >= nwg) return false; L = xcd_remap(L, nwg); }
;         int q; map_tile(L, nq, 65, u.pm, q);
;         if (set == 0) u.pn = q < 13 ? 4 + q : 26 + (q - 13);
;         else u.pn = q < 4 ? q : (q < 13 ? 17 + (q - 4) : 31 + (q - 13));
.LBB0_1280:
	s_add_i32 s23, s22, 1
	s_mul_i32 s10, s23, s15
	s_add_i32 s10, s10, s0
	s_cmpk_lt_i32 s10, 0xb2c
	s_cselect_b64 s[82:83], -1, 0
	s_cmpk_gt_i32 s10, 0xb2b
	s_cselect_b64 s[78:79], -1, 0
	s_and_b64 vcc, exec, s[78:79]
	s_cbranch_vccnz .LBB0_1288
	s_and_b32 s24, s10, 7
	s_mul_i32 s25, s24, 0x165
	s_min_u32 s24, s24, 4
	s_add_i32 s24, s25, s24
	s_nop 0
	s_ashr_i32 s10, s10, 3
	s_add_i32 s25, s24, s10
	s_mul_hi_i32 s10, s25, 0x5d1745d2
	s_lshr_b32 s24, s10, 31
	s_ashr_i32 s10, s10, 7
	s_add_i32 s27, s10, s24
	s_lshl_b32 s10, s27, 3
	s_sub_i32 s24, 0x41, s10
	s_min_u32 s24, s24, 8
	s_mulk_i32 s27, 0x160
	s_sub_i32 s25, s25, s27
	v_cvt_f32_ubyte0_e32 v144, s24
	v_cvt_f32_i32_e32 v136, s25
	v_rcp_iflag_f32_e32 v145, v144
	s_ashr_i32 s27, s25, 30
	s_or_b32 s27, s27, 1
	v_mul_f32_e32 v145, v136, v145
	v_trunc_f32_e32 v145, v145
	v_fma_f32 v136, -v145, v144, v136
	v_cvt_i32_f32_e32 v145, v145
	v_cmp_ge_f32_e64 s[28:29], |v136|, v144
	s_and_b64 s[28:29], s[28:29], exec
	s_cselect_b32 s27, s27, 0
	v_readfirstlane_b32 s28, v145
	s_add_i32 s27, s28, s27
	s_sext_i32_i16 s66, s27
	s_cmp_lt_i32 s66, 4
	s_cbranch_scc1 .LBB0_1287
	s_and_b32 s28, s66, 0xffff
	s_cmp_gt_u32 s28, 12
	s_mov_b64 s[68:69], -1
	s_cbranch_scc0 .LBB0_1284
	s_add_i32 s28, s66, 15
	s_mov_b64 s[68:69], 0

; __device__ __forceinline__ unsigned xb_ld(unsigned* p)              { return __hip_atomic_load(p, __ATOMIC_RELAXED, __HIP_MEMORY_SCOPE_AGENT); }
; __device__ __forceinline__ unsigned xb_add(unsigned* p, unsigned v) { return __hip_atomic_fetch_add(p, v, __ATOMIC_RELAXED, __HIP_MEMORY_SCOPE_AGENT); }
; #define XB_SPIN(cond, bar) do { unsigned _sp = 0; while (cond) { __builtin_amdgcn_s_sleep(1); \
;     if ((++_sp & 255u) == 0u) { if (xb_ld(&(bar)[XB_TMO])) break; if (_sp > XB_SPIN_CAP) { atomicAdd(&(bar)[XB_TMO], 1u); break; } } } } while (0)
; __device__ __forceinline__ void xcd_barrier(const XcdBarrier& b) {
;     ...
;         const unsigned old = xb_add(&bar[XB_XSUB(b.x)], 1u);
;         const unsigned gen = old / nloc;
;         if (old + 1u == (gen + 1u) * nloc) {
;             __builtin_amdgcn_fence(__ATOMIC_RELEASE, "agent");
;             asm volatile("s_waitcnt vmcnt(0)" ::: "memory");
;             const unsigned og = xb_add(&bar[XB_TOP], 1u);
;             const unsigned tg = og / nx;
;             if (og + 1u == (tg + 1u) * nx) xb_add(&bar[XB_TOPGEN], 1u);
;             else XB_SPIN(xb_ld(&bar[XB_TOPGEN]) == tg, bar);
;             __builtin_amdgcn_fence(__ATOMIC_ACQUIRE, "agent");
;             xb_add(&bar[XB_XGEN(b.x)], 1u);
;             asm volatile("s_waitcnt vmcnt(0)" ::: "memory");
;         } else {
;             XB_SPIN(xb_ld(&bar[XB_XGEN(b.x)]) == gen, bar);
.LBB0_1416:
	s_or_b64 exec, exec, s[10:11]
	v_cvt_f32_u32_e32 v4, v2
	s_waitcnt vmcnt(0)
	v_readfirstlane_b32 s0, v3
	v_sub_u32_e32 v3, 0, v2
	v_rcp_iflag_f32_e32 v4, v4
	v_add_u32_e32 v5, s0, v1
	v_mul_f32_e32 v4, 0x4f7ffffe, v4
	v_cvt_u32_f32_e32 v4, v4
	v_mul_lo_u32 v1, v3, v4
	v_mul_hi_u32 v1, v4, v1
	v_add_u32_e32 v1, v4, v1
	v_mul_hi_u32 v1, v5, v1
	v_mul_lo_u32 v3, v1, v2
	v_sub_u32_e32 v3, v5, v3
	v_add_u32_e32 v4, 1, v1
	v_cmp_ge_u32_e32 vcc, v3, v2
	s_nop 1
	v_cndmask_b32_e32 v1, v1, v4, vcc
	v_sub_u32_e32 v4, v3, v2
	v_cndmask_b32_e32 v3, v3, v4, vcc
	v_add_u32_e32 v4, 1, v1
	v_cmp_ge_u32_e32 vcc, v3, v2
	v_add_u32_e32 v3, 1, v5
	s_nop 0
	v_cndmask_b32_e32 v1, v1, v4, vcc
	v_mul_lo_u32 v4, v2, v1
	v_add_u32_e32 v2, v4, v2
	v_cmp_ne_u32_e32 vcc, v3, v2
	s_and_saveexec_b64 s[0:1], vcc
	s_xor_b64 s[8:9], exec, s[0:1]
	s_cbranch_execz .LBB0_1430
	s_waitcnt lgkmcnt(0)
	s_cmp_lt_i32 s92, 64
	s_cbranch_scc1 .LBB0_1430
	s_nop 0
	s_nop 0
	s_nop 0
	s_nop 0
	s_nop 0
	s_nop 0
	s_nop 0
	s_nop 0
	s_nop 0
	s_nop 0
	s_nop 0
	s_nop 0
	s_nop 0
	s_nop 0
	v_mov_b32_e32 v0, 0x2000
	global_load_dword v0, v0, s[6:7] offset:1024 sc1
	s_add_u32 s62, s6, 0x2400
	s_addc_u32 s63, s7, 0
	s_waitcnt vmcnt(0)
	v_cmp_eq_u32_e32 vcc, v0, v1
	s_and_saveexec_b64 s[10:11], vcc
	s_cbranch_execz .LBB0_1429
	s_mov_b32 s0, 1
	s_mov_b64 s[66:67], 0
	v_mov_b32_e32 v0, 0
	s_branch .LBB0_1420

; __device__ __forceinline__ float lo_bf(unsigned w) { return __uint_as_float(w << 16); }
; __device__ __forceinline__ float hi_bf(unsigned w) { return __uint_as_float(w & 0xffff0000u); }
; __device__ __forceinline__ void pool_item(const Params& P, int l, int item, unsigned char* smem) {
;     ...
; #pragma unroll
;                 for (int k = 0; k < WIN - 1 + 16; ++k) {
;                     const int dt = k - (WIN - 1), t = t0 + dt;
;                     if (t >= 0) { const unsigned wv = *(const unsigned*)(proj + (size_t)(R0 + dt) * NIN + c); u0[k] = lo_bf(wv); u1[k] = hi_bf(wv); }
;                     else if (hist) { const float* hp = hist + (size_t)(15 + t) * 1024 + c; u0[k] = hp[0]; u1[k] = hp[1]; }
;                     else { u0[k] = 0.f; u1[k] = 0.f; }
;                 }
.LBB0_1555:
	v_add_u32_e32 v32, -1, v39
	v_mad_i64_i32 v[32:33], s[10:11], v32, s15, v[0:1]
	global_load_dword v33, v[32:33], off
	s_waitcnt vmcnt(0)
	v_lshlrev_b32_e32 v4, 16, v5
	v_and_b32_e32 v5, 0xffff0000, v5
	v_lshlrev_b32_e32 v6, 16, v7
	v_and_b32_e32 v7, 0xffff0000, v7
	v_lshlrev_b32_e32 v8, 16, v9
	v_and_b32_e32 v9, 0xffff0000, v9
	v_lshlrev_b32_e32 v10, 16, v11
	v_and_b32_e32 v11, 0xffff0000, v11
	v_lshlrev_b32_e32 v12, 16, v13
	v_and_b32_e32 v13, 0xffff0000, v13
	v_lshlrev_b32_e32 v14, 16, v15
	v_and_b32_e32 v15, 0xffff0000, v15
	v_lshlrev_b32_e32 v16, 16, v17
	v_and_b32_e32 v17, 0xffff0000, v17
	v_lshlrev_b32_e32 v18, 16, v19
	v_and_b32_e32 v19, 0xffff0000, v19
	v_lshlrev_b32_e32 v20, 16, v21
	v_and_b32_e32 v21, 0xffff0000, v21
	v_lshlrev_b32_e32 v22, 16, v23
	v_and_b32_e32 v23, 0xffff0000, v23
	v_lshlrev_b32_e32 v24, 16, v25
	v_and_b32_e32 v25, 0xffff0000, v25
	v_lshlrev_b32_e32 v26, 16, v27
	v_and_b32_e32 v27, 0xffff0000, v27
	v_lshlrev_b32_e32 v28, 16, v29
	v_and_b32_e32 v29, 0xffff0000, v29
	v_lshlrev_b32_e32 v30, 16, v31
	v_and_b32_e32 v31, 0xffff0000, v31
	s_nop 0
	s_nop 0
	s_nop 0
	s_nop 0
	s_nop 0
	s_nop 0
	s_nop 0
	s_nop 0
	s_nop 0
	s_nop 0
	s_nop 0
	s_nop 0
	s_nop 0
	s_nop 0
	v_lshlrev_b32_e32 v32, 16, v33
	v_and_b32_e32 v33, 0xffff0000, v33
	s_andn2_saveexec_b64 s[6:7], s[6:7]
	s_cbranch_execz .LBB0_1521
	s_branch .LBB0_1613

; __device__ __forceinline__ float lo_bf(unsigned w) { return __uint_as_float(w << 16); }
; __device__ __forceinline__ float hi_bf(unsigned w) { return __uint_as_float(w & 0xffff0000u); }
; __device__ __forceinline__ void pool_item(const Params& P, int l, int item, unsigned char* smem) {
;     ...
; #pragma unroll
;                 for (int k = 0; k < WIN - 1 + 16; ++k) {
;                     const int dt = k - (WIN - 1), t = t0 + dt;
;                     if (t >= 0) { const unsigned wv = *(const unsigned*)(proj + (size_t)(R0 + dt) * NIN + c); u0[k] = lo_bf(wv); u1[k] = hi_bf(wv); }
;                     else if (hist) { const float* hp = hist + (size_t)(15 + t) * 1024 + c; u0[k] = hp[0]; u1[k] = hp[1]; }
;                     else { u0[k] = 0.f; u1[k] = 0.f; }
;                 }
.LBB0_1638:
	v_add_u32_e32 v16, -1, v22
	v_mad_i64_i32 v[16:17], s[10:11], v16, s15, v[0:1]
	global_load_dword v17, v[16:17], off
	s_waitcnt vmcnt(0)
	v_lshlrev_b32_e32 v4, 16, v5
	v_and_b32_e32 v5, 0xffff0000, v5
	v_lshlrev_b32_e32 v6, 16, v7
	v_and_b32_e32 v7, 0xffff0000, v7
	v_lshlrev_b32_e32 v8, 16, v9
	v_and_b32_e32 v9, 0xffff0000, v9
	v_lshlrev_b32_e32 v10, 16, v11
	v_and_b32_e32 v11, 0xffff0000, v11
	v_lshlrev_b32_e32 v12, 16, v13
	v_and_b32_e32 v13, 0xffff0000, v13
	v_lshlrev_b32_e32 v14, 16, v15
	v_and_b32_e32 v15, 0xffff0000, v15
	s_nop 0
	s_nop 0
	s_nop 0
	s_nop 0
	s_nop 0
	s_nop 0
	v_lshlrev_b32_e32 v16, 16, v17
	v_and_b32_e32 v17, 0xffff0000, v17
	s_andn2_saveexec_b64 s[6:7], s[6:7]
	s_cbranch_execz .LBB0_1620
	s_branch .LBB0_1664

; __device__ __forceinline__ float lo_bf(unsigned w) { return __uint_as_float(w << 16); }
; __device__ __forceinline__ float hi_bf(unsigned w) { return __uint_as_float(w & 0xffff0000u); }
; __device__ __forceinline__ void pool_item(const Params& P, int l, int item, unsigned char* smem) {
;     ...
;                 float u0[WIN - 1 + 16], u1[WIN - 1 + 16];
; #pragma unroll
;                 for (int k = 0; k < WIN - 1 + 16; ++k) {
;                     const int dt = k - (WIN - 1), t = t0 + dt;
;                     if (t >= 0) { const unsigned wv = *(const unsigned*)(proj + (size_t)(R0 + dt) * NIN + c); u0[k] = lo_bf(wv); u1[k] = hi_bf(wv); }
;                     else if (hist) { const float* hp = hist + (size_t)(15 + t) * 1024 + c; u0[k] = hp[0]; u1[k] = hp[1]; }
;                     else { u0[k] = 0.f; u1[k] = 0.f; }
;                 }
.LBB0_1695:
	v_add_u32_e32 v8, -1, v14
	v_mad_i64_i32 v[8:9], s[10:11], v8, s15, v[0:1]
	global_load_dword v9, v[8:9], off
	s_waitcnt vmcnt(0)
	v_lshlrev_b32_e32 v4, 16, v5
	v_and_b32_e32 v5, 0xffff0000, v5
	v_lshlrev_b32_e32 v6, 16, v7
	v_and_b32_e32 v7, 0xffff0000, v7
	s_nop 0
	s_nop 0
	v_lshlrev_b32_e32 v8, 16, v9
	v_and_b32_e32 v9, 0xffff0000, v9
	s_andn2_saveexec_b64 s[6:7], s[6:7]
	s_cbranch_execz .LBB0_1685
	s_branch .LBB0_1705

; __device__ __forceinline__ unsigned xb_ld(unsigned* p)              { return __hip_atomic_load(p, __ATOMIC_RELAXED, __HIP_MEMORY_SCOPE_AGENT); }
; #define XB_SPIN(cond, bar) do { unsigned _sp = 0; while (cond) { __builtin_amdgcn_s_sleep(1); \
;     if ((++_sp & 255u) == 0u) { if (xb_ld(&(bar)[XB_TMO])) break; if (_sp > XB_SPIN_CAP) { atomicAdd(&(bar)[XB_TMO], 1u); break; } } } } while (0)
; __device__ __forceinline__ void xcd_barrier(const XcdBarrier& b) {
;     ...
;         } else {
;             XB_SPIN(xb_ld(&bar[XB_XGEN(b.x)]) == gen, bar);
;             __builtin_amdgcn_fence(__ATOMIC_ACQUIRE, "agent");
;             asm volatile("s_waitcnt vmcnt(0)" ::: "memory");
;         }
.Lb2wait_l1:
	s_nop 0
	s_nop 0
	s_nop 0
	s_nop 0
	s_nop 0
	s_nop 0
	s_nop 0
	s_nop 0
	s_nop 0
	s_nop 0
	s_nop 0
	s_nop 0
	v_mov_b32_e32 v0, 0x2000
	global_load_dword v0, v0, s[6:7] offset:1024 sc1
	s_add_u32 s12, s6, 0x2400
	s_addc_u32 s13, s7, 0
	s_waitcnt vmcnt(0)
	v_cmp_eq_u32_e32 vcc, v0, v1
	s_and_saveexec_b64 s[10:11], vcc
	s_cbranch_execz .LBB0_2849
	s_mov_b32 s2, 1
	s_mov_b64 s[30:31], 0
	v_mov_b32_e32 v0, 0
	s_branch .LBB0_2840

;     __device__ __forceinline__ bool next(int i, Unit& u) {
;         const int nq = set == 0 ? 18 : 41, nwg = 65 * nq;
;         int L;
;         if (ctr) {
;             if (t0) {
;                 const int q8 = nwg >> 3, r8 = nwg & 7;
;                 int res = nwg;
;                 while (steal < 8) {
;                     const int x = (c + steal) & 7;
;                     const int cnt = q8 + (x < r8 ? 1 : 0), base = x < r8 ? x * (q8 + 1) : r8 * (q8 + 1) + (x - r8) * q8;
;                     const int v = (int)atomicAdd(ctr + x, 1u);
;                     if (v < cnt) { res = base + v; break; }
;                     ++steal;
;                 }
;                 slot[i & 1] = res; asm volatile("s_waitcnt lgkmcnt(0)" ::: "memory");
;             }
;             __builtin_amdgcn_s_barrier();
;             asm volatile("" ::: "memory");
;             L = slot[i & 1];
;             if (L >= nwg) return false;
;         } else { L = i * G + c; if (L >= nwg) return false; L = xcd_remap(L, nwg); }
;         int q; map_tile(L, nq, 65, u.pm, q);
;         if (set == 0) u.pn = q < 13 ? 4 + q : 26 + (q - 13);
;         else u.pn = q < 4 ? q : (q < 13 ? 17 + (q - 4) : 31 + (q - 13));
;         u.z = 0; return true;
.LBB0_3576:
	s_cmp_gt_i32 s92, 63
	s_cselect_b64 s[6:7], -1, 0
	s_mov_b64 s[0:1], -1
	s_and_b64 vcc, exec, s[6:7]
	s_cbranch_vccz .LBB0_3691
	s_mov_b64 s[0:1], src_shared_base
	s_getreg_b32 s0, hwreg(HW_REG_HW_ID, 0, 6)
	s_and_b32 s0, s0, 63
	s_lshl_b32 s0, s0, 2
	s_add_i32 s0, s0, 0
	s_add_i32 s0, s0, 0x20100
	v_mov_b32_e32 v0, s0
	v_mov_b32_e32 v1, s1
	flat_load_dword v0, v[0:1] sc0 sc1
	s_waitcnt vmcnt(0)
	s_sub_i32 s2, s92, 64
	s_cmpk_lt_u32 s2, 0xb2c
	s_cselect_b64 s[10:11], -1, 0
	s_cmpk_gt_u32 s2, 0xb2b
	s_waitcnt lgkmcnt(0)
	v_readfirstlane_b32 s0, v0
	s_nop 1
	v_lshl_or_b32 v8, s0, 6, v214
	s_nop 0
	v_readfirstlane_b32 s3, v8
	s_cbranch_scc1 .LBB0_3586
	s_and_b32 s0, s92, 7
	s_mul_i32 s1, s0, 0x165
	s_min_u32 s0, s0, 4
	s_add_i32 s0, s1, s0
	s_nop 0
	s_lshr_b32 s1, s2, 3
	s_add_i32 s0, s0, s1
	s_bfe_u32 s1, s0, 0xb0005
	s_mulk_i32 s1, 0x2e8c
	s_lshr_b32 s1, s1, 17
	s_lshl_b32 s4, s1, 3
	s_sub_i32 s5, 0x41, s4
	s_mulk_i32 s1, 0x160
	s_min_u32 s5, s5, 8
	s_sub_i32 s8, s0, s1
	s_and_b32 s0, s8, 0xffff
	v_cvt_f32_ubyte0_e32 v1, s5
	v_cvt_f32_u32_e32 v0, s0
	v_rcp_iflag_f32_e32 v2, v1
	s_nop 0
	v_mul_f32_e32 v2, v0, v2
	v_trunc_f32_e32 v2, v2
	v_cvt_u32_f32_e32 v3, v2
	v_fma_f32 v0, -v2, v1, v0
	v_cmp_ge_f32_e64 s[0:1], |v0|, v1
	s_cmp_lg_u64 s[0:1], 0
	v_readfirstlane_b32 s9, v3
	s_addc_u32 s1, s9, 0
	s_and_b32 s0, s1, 0xffff
	s_mul_i32 s1, s1, s5
	s_sub_i32 s1, s8, s1
	s_add_i32 s1, s1, s4
	s_cmp_lt_u32 s0, 4
	s_cbranch_scc1 .LBB0_3585
	s_cmp_gt_u32 s0, 12
	s_cbranch_scc0 .LBB0_3581
	s_add_i32 s4, s0, 15
	s_mov_b64 s[8:9], 0
	s_branch .LBB0_3582

;     __device__ __forceinline__ bool next(int i, Unit& u) {
;         const int nq = set == 0 ? 18 : 41, nwg = 65 * nq;
;         int L;
;         if (ctr) {
;             if (t0) {
;                 const int q8 = nwg >> 3, r8 = nwg & 7;
;                 int res = nwg;
;                 while (steal < 8) {
;                     const int x = (c + steal) & 7;
;                     const int cnt = q8 + (x < r8 ? 1 : 0), base = x < r8 ? x * (q8 + 1) : r8 * (q8 + 1) + (x - r8) * q8;
;                     const int v = (int)atomicAdd(ctr + x, 1u);
;                     if (v < cnt) { res = base + v; break; }
;                     ++steal;
;                 }
;                 slot[i & 1] = res; asm volatile("s_waitcnt lgkmcnt(0)" ::: "memory");
;             }
;             __builtin_amdgcn_s_barrier();
;             asm volatile("" ::: "memory");
;             L = slot[i & 1];
;             if (L >= nwg) return false;
;         } else { L = i * G + c; if (L >= nwg) return false; L = xcd_remap(L, nwg); }
;         int q; map_tile(L, nq, 65, u.pm, q);
;         if (set == 0) u.pn = q < 13 ? 4 + q : 26 + (q - 13);
;         else u.pn = q < 4 ? q : (q < 13 ? 17 + (q - 4) : 31 + (q - 13));
;         u.z = 0; return true;
.LBB0_3591:
	s_add_i32 s80, s29, 1
	s_mul_i32 s4, s80, s21
	s_add_i32 s4, s4, s2
	s_cmpk_lt_i32 s4, 0xb2c
	s_cselect_b64 s[64:65], -1, 0
	s_cmpk_gt_i32 s4, 0xb2b
	s_cselect_b64 s[60:61], -1, 0
	s_and_b64 vcc, exec, s[60:61]
	s_cbranch_vccnz .LBB0_3599
	s_and_b32 s5, s4, 7
	s_mul_i32 s12, s5, 0x165
	s_min_u32 s5, s5, 4
	s_add_i32 s5, s12, s5
	s_nop 0
	s_ashr_i32 s4, s4, 3
	s_add_i32 s12, s5, s4
	s_mul_hi_i32 s4, s12, 0x5d1745d2
	s_lshr_b32 s5, s4, 31
	s_ashr_i32 s4, s4, 7
	s_add_i32 s52, s4, s5
	s_lshl_b32 s4, s52, 3
	s_sub_i32 s5, 0x41, s4
	s_min_u32 s5, s5, 8
	s_mulk_i32 s52, 0x160
	s_sub_i32 s12, s12, s52
	v_cvt_f32_ubyte0_e32 v144, s5
	v_cvt_f32_i32_e32 v136, s12
	v_rcp_iflag_f32_e32 v145, v144
	s_ashr_i32 s52, s12, 30
	s_or_b32 s54, s52, 1
	v_mul_f32_e32 v145, v136, v145
	v_trunc_f32_e32 v145, v145
	v_fma_f32 v136, -v145, v144, v136
	v_cvt_i32_f32_e32 v145, v145
	v_cmp_ge_f32_e64 s[52:53], |v136|, v144
	s_and_b64 s[52:53], s[52:53], exec
	s_cselect_b32 s52, s54, 0
	v_readfirstlane_b32 s53, v145
	s_add_i32 s53, s53, s52
	s_sext_i32_i16 s52, s53
	s_cmp_lt_i32 s52, 4
	s_cbranch_scc1 .LBB0_3598
	s_and_b32 s54, s52, 0xffff
	s_cmp_gt_u32 s54, 12
	s_mov_b64 s[54:55], -1
	s_cbranch_scc0 .LBB0_3595
	s_add_i32 s62, s52, 15
	s_mov_b64 s[54:55], 0

; __device__ __forceinline__ unsigned xb_ld(unsigned* p)              { return __hip_atomic_load(p, __ATOMIC_RELAXED, __HIP_MEMORY_SCOPE_AGENT); }
; __device__ __forceinline__ unsigned xb_add(unsigned* p, unsigned v) { return __hip_atomic_fetch_add(p, v, __ATOMIC_RELAXED, __HIP_MEMORY_SCOPE_AGENT); }
; #define XB_SPIN(cond, bar) do { unsigned _sp = 0; while (cond) { __builtin_amdgcn_s_sleep(1); \
;     if ((++_sp & 255u) == 0u) { if (xb_ld(&(bar)[XB_TMO])) break; if (_sp > XB_SPIN_CAP) { atomicAdd(&(bar)[XB_TMO], 1u); break; } } } } while (0)
; __device__ __forceinline__ void xcd_barrier(const XcdBarrier& b) {
;     ...
;         const unsigned old = xb_add(&bar[XB_XSUB(b.x)], 1u);
;         const unsigned gen = old / nloc;
;         if (old + 1u == (gen + 1u) * nloc) {
;             __builtin_amdgcn_fence(__ATOMIC_RELEASE, "agent");
;             asm volatile("s_waitcnt vmcnt(0)" ::: "memory");
;             const unsigned og = xb_add(&bar[XB_TOP], 1u);
;             const unsigned tg = og / nx;
;             if (og + 1u == (tg + 1u) * nx) xb_add(&bar[XB_TOPGEN], 1u);
;             else XB_SPIN(xb_ld(&bar[XB_TOPGEN]) == tg, bar);
;             __builtin_amdgcn_fence(__ATOMIC_ACQUIRE, "agent");
;             xb_add(&bar[XB_XGEN(b.x)], 1u);
;             asm volatile("s_waitcnt vmcnt(0)" ::: "memory");
;         } else {
;             XB_SPIN(xb_ld(&bar[XB_XGEN(b.x)]) == gen, bar);
;             __builtin_amdgcn_fence(__ATOMIC_ACQUIRE, "agent");
;             asm volatile("s_waitcnt vmcnt(0)" ::: "memory");
;         }
.LBB0_3727:
	s_or_b64 exec, exec, s[12:13]
	v_cvt_f32_u32_e32 v4, v2
	s_waitcnt vmcnt(0)
	v_readfirstlane_b32 s2, v3
	v_sub_u32_e32 v3, 0, v2
	v_rcp_iflag_f32_e32 v4, v4
	v_add_u32_e32 v5, s2, v1
	v_mul_f32_e32 v4, 0x4f7ffffe, v4
	v_cvt_u32_f32_e32 v4, v4
	v_mul_lo_u32 v1, v3, v4
	v_mul_hi_u32 v1, v4, v1
	v_add_u32_e32 v1, v4, v1
	v_mul_hi_u32 v1, v5, v1
	v_mul_lo_u32 v3, v1, v2
	v_sub_u32_e32 v3, v5, v3
	v_add_u32_e32 v4, 1, v1
	v_cmp_ge_u32_e32 vcc, v3, v2
	s_nop 1
	v_cndmask_b32_e32 v1, v1, v4, vcc
	v_sub_u32_e32 v4, v3, v2
	v_cndmask_b32_e32 v3, v3, v4, vcc
	v_add_u32_e32 v4, 1, v1
	v_cmp_ge_u32_e32 vcc, v3, v2
	v_add_u32_e32 v3, 1, v5
	s_nop 0
	v_cndmask_b32_e32 v1, v1, v4, vcc
	v_mul_lo_u32 v4, v2, v1
	v_add_u32_e32 v2, v4, v2
	v_cmp_ne_u32_e32 vcc, v3, v2
	s_and_saveexec_b64 s[2:3], vcc
	s_xor_b64 s[10:11], exec, s[2:3]
	s_cbranch_execz .LBB0_3741
	s_waitcnt lgkmcnt(0)
	s_cmp_lt_i32 s92, 64
	s_cbranch_scc1 .LBB0_3741
	s_nop 0
	s_nop 0
	s_nop 0
	s_nop 0
	s_nop 0
	s_nop 0
	s_nop 0
	s_nop 0
	s_nop 0
	s_nop 0
	s_nop 0
	s_nop 0
	s_nop 0
	s_nop 0
	v_mov_b32_e32 v0, 0x2000
	global_load_dword v0, v0, s[8:9] offset:1024 sc1
	s_add_u32 s18, s8, 0x2400
	s_addc_u32 s19, s9, 0
	s_waitcnt vmcnt(0)
	v_cmp_eq_u32_e32 vcc, v0, v1
	s_and_saveexec_b64 s[12:13], vcc
	s_cbranch_execz .LBB0_3740
	s_mov_b32 s2, 1
	s_mov_b64 s[30:31], 0
	v_mov_b32_e32 v0, 0
	s_branch .LBB0_3731

; __device__ __forceinline__ float lo_bf(unsigned w) { return __uint_as_float(w << 16); }
; __device__ __forceinline__ float hi_bf(unsigned w) { return __uint_as_float(w & 0xffff0000u); }
; __device__ __forceinline__ void pool_item(const Params& P, int l, int item, unsigned char* smem) {
;     ...
;                 float u0[WIN - 1 + 16], u1[WIN - 1 + 16];
; #pragma unroll
;                 for (int k = 0; k < WIN - 1 + 16; ++k) {
;                     const int dt = k - (WIN - 1), t = t0 + dt;
;                     if (t >= 0) { const unsigned wv = *(const unsigned*)(proj + (size_t)(R0 + dt) * NIN + c); u0[k] = lo_bf(wv); u1[k] = hi_bf(wv); }
;                     else if (hist) { const float* hp = hist + (size_t)(15 + t) * 1024 + c; u0[k] = hp[0]; u1[k] = hp[1]; }
;                     else { u0[k] = 0.f; u1[k] = 0.f; }
;                 }
.LBB0_3862:
	v_add_u32_e32 v18, -1, v39
	v_mad_i64_i32 v[18:19], s[4:5], v18, s21, v[0:1]
	global_load_dword v18, v[18:19], off
	s_waitcnt vmcnt(0)
	v_lshlrev_b32_e32 v4, 16, v5
	v_and_b32_e32 v5, 0xffff0000, v5
	v_lshlrev_b32_e32 v6, 16, v7
	v_and_b32_e32 v7, 0xffff0000, v7
	v_lshlrev_b32_e32 v8, 16, v9
	v_and_b32_e32 v9, 0xffff0000, v9
	v_lshlrev_b32_e32 v10, 16, v11
	v_and_b32_e32 v11, 0xffff0000, v11
	v_lshlrev_b32_e32 v12, 16, v13
	v_and_b32_e32 v13, 0xffff0000, v13
	v_lshlrev_b32_e32 v14, 16, v15
	v_and_b32_e32 v15, 0xffff0000, v15
	v_lshlrev_b32_e32 v16, 16, v17
	v_and_b32_e32 v17, 0xffff0000, v17
	v_lshlrev_b32_e32 v20, 16, v21
	v_and_b32_e32 v21, 0xffff0000, v21
	v_lshlrev_b32_e32 v22, 16, v23
	v_and_b32_e32 v23, 0xffff0000, v23
	v_lshlrev_b32_e32 v24, 16, v25
	v_and_b32_e32 v25, 0xffff0000, v25
	v_lshlrev_b32_e32 v26, 16, v27
	v_and_b32_e32 v27, 0xffff0000, v27
	v_lshlrev_b32_e32 v28, 16, v29
	v_and_b32_e32 v29, 0xffff0000, v29
	v_lshlrev_b32_e32 v30, 16, v31
	v_and_b32_e32 v31, 0xffff0000, v31
	v_lshlrev_b32_e32 v32, 16, v33
	v_and_b32_e32 v33, 0xffff0000, v33
	s_nop 0
	s_nop 0
	s_nop 0
	s_nop 0
	s_nop 0
	s_nop 0
	s_nop 0
	s_nop 0
	s_nop 0
	s_nop 0
	s_nop 0
	s_nop 0
	s_nop 0
	s_nop 0
	v_lshlrev_b32_e32 v34, 16, v18
	v_and_b32_e32 v35, 0xffff0000, v18
	s_andn2_saveexec_b64 s[8:9], s[8:9]
	s_cbranch_execz .LBB0_3828
	s_branch .LBB0_3920

; __device__ __forceinline__ float lo_bf(unsigned w) { return __uint_as_float(w << 16); }
; __device__ __forceinline__ float hi_bf(unsigned w) { return __uint_as_float(w & 0xffff0000u); }
; __device__ __forceinline__ void pool_item(const Params& P, int l, int item, unsigned char* smem) {
;     ...
;                 float u0[WIN - 1 + 16], u1[WIN - 1 + 16];
; #pragma unroll
;                 for (int k = 0; k < WIN - 1 + 16; ++k) {
;                     const int dt = k - (WIN - 1), t = t0 + dt;
;                     if (t >= 0) { const unsigned wv = *(const unsigned*)(proj + (size_t)(R0 + dt) * NIN + c); u0[k] = lo_bf(wv); u1[k] = hi_bf(wv); }
;                     else if (hist) { const float* hp = hist + (size_t)(15 + t) * 1024 + c; u0[k] = hp[0]; u1[k] = hp[1]; }
;                     else { u0[k] = 0.f; u1[k] = 0.f; }
;                 }
.LBB0_3945:
	v_add_u32_e32 v16, -1, v22
	v_mad_i64_i32 v[16:17], s[4:5], v16, s21, v[0:1]
	global_load_dword v16, v[16:17], off
	s_waitcnt vmcnt(0)
	v_lshlrev_b32_e32 v4, 16, v5
	v_and_b32_e32 v5, 0xffff0000, v5
	v_lshlrev_b32_e32 v6, 16, v7
	v_and_b32_e32 v7, 0xffff0000, v7
	v_lshlrev_b32_e32 v8, 16, v9
	v_and_b32_e32 v9, 0xffff0000, v9
	v_lshlrev_b32_e32 v10, 16, v11
	v_and_b32_e32 v11, 0xffff0000, v11
	v_lshlrev_b32_e32 v12, 16, v13
	v_and_b32_e32 v13, 0xffff0000, v13
	v_lshlrev_b32_e32 v14, 16, v15
	v_and_b32_e32 v15, 0xffff0000, v15
	s_nop 0
	s_nop 0
	s_nop 0
	s_nop 0
	s_nop 0
	s_nop 0
	v_lshlrev_b32_e32 v18, 16, v16
	v_and_b32_e32 v19, 0xffff0000, v16
	s_andn2_saveexec_b64 s[8:9], s[8:9]
	s_cbranch_execz .LBB0_3927
	s_branch .LBB0_3971

; __device__ __forceinline__ float lo_bf(unsigned w) { return __uint_as_float(w << 16); }
; __device__ __forceinline__ float hi_bf(unsigned w) { return __uint_as_float(w & 0xffff0000u); }
; __device__ __forceinline__ void pool_item(const Params& P, int l, int item, unsigned char* smem) {
;     ...
;                 float u0[WIN - 1 + 16], u1[WIN - 1 + 16];
; #pragma unroll
;                 for (int k = 0; k < WIN - 1 + 16; ++k) {
;                     const int dt = k - (WIN - 1), t = t0 + dt;
;                     if (t >= 0) { const unsigned wv = *(const unsigned*)(proj + (size_t)(R0 + dt) * NIN + c); u0[k] = lo_bf(wv); u1[k] = hi_bf(wv); }
;                     else if (hist) { const float* hp = hist + (size_t)(15 + t) * 1024 + c; u0[k] = hp[0]; u1[k] = hp[1]; }
;                     else { u0[k] = 0.f; u1[k] = 0.f; }
;                 }
.LBB0_4002:
	v_add_u32_e32 v8, -1, v14
	v_mad_i64_i32 v[8:9], s[4:5], v8, s21, v[0:1]
	global_load_dword v9, v[8:9], off
	s_waitcnt vmcnt(0)
	v_lshlrev_b32_e32 v4, 16, v5
	v_and_b32_e32 v5, 0xffff0000, v5
	v_lshlrev_b32_e32 v6, 16, v7
	v_and_b32_e32 v7, 0xffff0000, v7
	s_nop 0
	s_nop 0
	v_lshlrev_b32_e32 v8, 16, v9
	v_and_b32_e32 v9, 0xffff0000, v9
	s_andn2_saveexec_b64 s[8:9], s[8:9]
	s_cbranch_execz .LBB0_3992
	s_branch .LBB0_4012
